# ssm pass2 loop software-pipelined: next group's Bu MFMAs and tile writes overlap the current group's scan
# baseline (speedup 1.0000x reference)
; __device__ __forceinline__ void ssm_ops_load(SsmOps& S, const float* ABAR, const bf16_t* BBH, const bf16_t* BBL, int g, int lane) {
;     ...
;     for (int nb = 0; nb < 8; ++nb) { const size_t o = (size_t)(g * 128 + 16 * nb + fr) * 16 + (fq & 1) * 8;
;         const bf16x8 h = *(const bf16x8*)(BBH + o); S.bh[nb] = fq < 2 ? h : z; }
; __device__ __forceinline__ void ssm_pass2(LAS unsigned char* lds, const bf16_t* US, const float* SST, bf16_t* YB, const float* ABAR, const bf16_t* BBH, const bf16_t* BBL, const bf16_t* CMH, const bf16_t* CML, const float* dco, int gw, int NGW, int lane, int wave) {
;     ...
;         for (int ks = 0; ks < 4; ++ks) { const size_t o = (size_t)(g * 16 + fr) * 128 + ks * 32 + fq * 8; ch[ks] = *(const bf16x8*)(CMH + o); }
;         const float dh = dco[g * 16 + fr];
;         float pr = S.ar, pi = S.ai;
; #pragma unroll
;         for (int s = 0; s < 8; ++s) { const float nr = pr * pr - pi * pi, ni = 2.f * pr * pi; pr = nr; pi = ni; }
;         float xr = 0.f, xi = 0.f;
;         { float sr[7], sm[7];
; #pragma unroll
;           for (int cc = 0; cc < 7; ++cc) { const float* si = SST + ((size_t)bg * 8 + (cc < c ? cc : 0)) * 128; sr[cc] = si[lane]; sm[cc] = si[64 + lane]; }
; #pragma unroll
;           for (int cc = 0; cc < 7; ++cc) if (cc < c) { const float nr = pr * xr - pi * xi + sr[cc], ni = pr * xi + pi * xr + sm[cc]; xr = nr; xi = ni; } }
;         const int tokc = b * SEQ + c * 256;
;         bf16x8 uh; ssm_u_load(uh, US, tokc, g, lane);
.LBB0_549:
	s_and_b32 s21, s68, 0xfffff800
	v_or_b32_e32 v125, s21, v120
	v_or_b32_e32 v126, s21, v121
	s_lshl_b32 s21, s70, 3
	v_mul_f32_e32 v48, v66, v52
	s_and_b32 s21, s21, 0xfffff800
	v_fma_f32 v48, v65, v53, -v48
	s_or_b32 s59, s21, s3
	v_add_f32_e32 v68, v50, v48
	v_or_b32_e32 v48, s59, v114
	v_ashrrev_i32_e32 v49, 31, v48
	v_lshlrev_b64 v[48:49], 10, v[48:49]
	v_lshl_add_u64 v[48:49], s[46:47], 0, v[48:49]
	s_lshl_b32 s20, s20, 1
	s_mov_b32 s21, s57
	v_lshl_add_u64 v[48:49], v[48:49], 0, s[20:21]
	v_lshl_add_u64 v[48:49], v[48:49], 0, v[80:81]
	global_load_dwordx4 v[48:51], v[48:49], off
	v_mul_f32_e32 v67, v66, v53
	v_fmac_f32_e32 v67, v65, v52
	v_add_f32_e32 v64, v64, v67
	v_cndmask_b32_e64 v52, v52, v64, s[8:9]
	v_cndmask_b32_e64 v53, v53, v68, s[8:9]
	v_mul_f32_e32 v64, v66, v53
	v_mul_f32_e32 v67, v66, v52
	v_fmac_f32_e32 v64, v65, v52
	v_fma_f32 v67, v65, v53, -v67
	v_add_f32_e32 v62, v62, v67
	v_add_f32_e32 v63, v63, v64
	v_cndmask_b32_e64 v52, v52, v63, s[10:11]
	v_cndmask_b32_e64 v53, v53, v62, s[10:11]
	v_mul_f32_e32 v62, v66, v53
	v_mul_f32_e32 v63, v66, v52
	v_fmac_f32_e32 v62, v65, v52
	v_fma_f32 v63, v65, v53, -v63
	v_add_f32_e32 v60, v60, v63
	v_add_f32_e32 v61, v61, v62
	v_cndmask_b32_e64 v52, v52, v61, s[12:13]
	v_cndmask_b32_e64 v53, v53, v60, s[12:13]
	v_mul_f32_e32 v60, v66, v53
	v_mul_f32_e32 v61, v66, v52
	v_fmac_f32_e32 v60, v65, v52
	v_fma_f32 v61, v65, v53, -v61
	v_add_f32_e32 v56, v56, v61
	v_add_f32_e32 v57, v57, v60
	v_cndmask_b32_e64 v52, v52, v57, s[14:15]
	v_cndmask_b32_e64 v53, v53, v56, s[14:15]
	v_mul_f32_e32 v56, v66, v53
	v_mul_f32_e32 v57, v66, v52
	v_fmac_f32_e32 v56, v65, v52
	v_fma_f32 v57, v65, v53, -v57
	v_add_f32_e32 v57, v58, v57
	v_add_f32_e32 v56, v59, v56
	v_cndmask_b32_e64 v52, v52, v56, s[16:17]
	v_cndmask_b32_e64 v53, v53, v57, s[16:17]
	v_mul_f32_e32 v56, v66, v53
	v_mul_f32_e32 v57, v66, v52
	v_fmac_f32_e32 v56, v65, v52
	v_fma_f32 v57, v65, v53, -v57
	v_add_f32_e32 v54, v54, v57
	v_add_f32_e32 v55, v55, v56
	v_pk_mov_b32 v[94:95], v[90:91], v[90:91] op_sel:[1,0]
	v_cndmask_b32_e64 v76, v52, v55, s[18:19]
	v_cndmask_b32_e64 v100, v53, v54, s[18:19]
	v_cndmask_b32_e64 v19, 0, v19, s[4:5]
	v_cndmask_b32_e64 v18, 0, v18, s[4:5]
	v_cndmask_b32_e64 v17, 0, v17, s[4:5]
	v_cndmask_b32_e64 v16, 0, v16, s[4:5]
	v_cndmask_b32_e64 v23, 0, v23, s[4:5]
	v_cndmask_b32_e64 v22, 0, v22, s[4:5]
	v_cndmask_b32_e64 v21, 0, v21, s[4:5]
	v_cndmask_b32_e64 v20, 0, v20, s[4:5]
	v_cndmask_b32_e64 v27, 0, v27, s[4:5]
	v_cndmask_b32_e64 v26, 0, v26, s[4:5]
	v_cndmask_b32_e64 v25, 0, v25, s[4:5]
	v_cndmask_b32_e64 v24, 0, v24, s[4:5]
	v_cndmask_b32_e64 v31, 0, v31, s[4:5]
	v_cndmask_b32_e64 v30, 0, v30, s[4:5]
	v_cndmask_b32_e64 v29, 0, v29, s[4:5]
	v_cndmask_b32_e64 v28, 0, v28, s[4:5]
	v_cndmask_b32_e64 v35, 0, v35, s[4:5]
	v_cndmask_b32_e64 v34, 0, v34, s[4:5]
	v_cndmask_b32_e64 v33, 0, v33, s[4:5]
	v_cndmask_b32_e64 v32, 0, v32, s[4:5]
	v_cndmask_b32_e64 v39, 0, v39, s[4:5]
	v_cndmask_b32_e64 v38, 0, v38, s[4:5]
	v_cndmask_b32_e64 v37, 0, v37, s[4:5]
	v_cndmask_b32_e64 v36, 0, v36, s[4:5]
	v_cndmask_b32_e64 v43, 0, v43, s[4:5]
	v_cndmask_b32_e64 v42, 0, v42, s[4:5]
	v_cndmask_b32_e64 v41, 0, v41, s[4:5]
	v_cndmask_b32_e64 v40, 0, v40, s[4:5]
	v_cndmask_b32_e64 v47, 0, v47, s[4:5]
	v_cndmask_b32_e64 v46, 0, v46, s[4:5]
	v_cndmask_b32_e64 v45, 0, v45, s[4:5]
	v_cndmask_b32_e64 v44, 0, v44, s[4:5]
	v_lshl_add_u64 v[98:99], v[84:85], 0, s[20:21]
	v_lshl_add_u64 v[96:97], v[86:87], 0, s[20:21]
	v_lshl_add_u64 v[92:93], v[88:89], 0, s[20:21]
	v_readlane_b32 s98, v249, 18
	s_mov_b32 s100, 0x4000
	s_mov_b32 s101, 0
	s_lshl_b32 s99, s20, 7
	s_mul_i32 s98, s98, 0x3a00
	v_lshrrev_b32_e32 v109, 4, v196
	v_mul_u32_u24_e32 v144, 0x50, v114
	v_lshl_add_u32 v144, v109, 4, v144
	v_add_u32_e32 v144, s98, v144
	v_mul_u32_u24_e32 v145, 0x50, v196
	v_add_u32_e32 v145, s98, v145
	v_lshl_add_u32 v146, v196, 2, s98
	v_add_u32_e32 v146, 0x2800, v146
	v_mul_u32_u24_e32 v147, 0x120, v114
	v_lshl_add_u32 v147, v109, 4, v147
	v_add_u32_e32 v147, s98, v147
	v_add_u32_e32 v147, 0x2800, v147
	v_xor_b32_e32 v77, 0x80000000, v91
	v_add_u32_e32 v108, s59, v114
	v_add_u32_e32 v108, 16, v108
	v_lshlrev_b32_e32 v108, 10, v108
	v_mov_b32_e32 v111, 0
	v_mov_b32_e32 v112, v108
	v_mov_b32_e32 v113, v111
	v_lshl_add_u64 v[148:149], v[98:99], 0, v[112:113]
	global_load_dwordx4 v[56:59], v[148:149], off
	v_lshl_add_u64 v[148:149], v[148:149], 0, s[100:101]
	v_lshlrev_b32_e32 v110, 8, v114
	v_lshl_add_u32 v110, v109, 3, v110
	v_add_u32_e32 v110, s99, v110
	global_load_dwordx2 v[230:231], v110, s[54:55] offset:0
	global_load_dwordx2 v[232:233], v110, s[54:55] offset:128
	global_load_dwordx2 v[234:235], v110, s[54:55] offset:32
	global_load_dwordx2 v[236:237], v110, s[54:55] offset:160
	global_load_dwordx2 v[238:239], v110, s[54:55] offset:64
	global_load_dwordx2 v[240:241], v110, s[54:55] offset:192
	global_load_dwordx2 v[242:243], v110, s[54:55] offset:96
	global_load_dwordx2 v[244:245], v110, s[54:55] offset:224
	v_mov_b32_e32 v109, 0
	v_lshrrev_b32_e32 v108, 4, v196
	v_lshl_add_u32 v108, v108, 2, s59
	v_lshlrev_b32_e32 v108, 10, v108
	v_lshl_add_u64 v[150:151], v[92:93], 0, v[108:109]
	s_mov_b32 s99, 0xffff0000
	s_mov_b32 s20, 0
	s_waitcnt vmcnt(0)
; #define LAS __attribute__((address_space(3)))
; __device__ __forceinline__ void ssm_bu_tile(const SsmOps& S, bf16x8 uh, LAS float* tile, int lane) {
;     ...
;     if (fq >= 2) uh = (bf16x8){0, 0, 0, 0, 0, 0, 0, 0};
; #pragma unroll
;     for (int nb = 0; nb < 8; ++nb) { f32x4 acc = {0.f, 0.f, 0.f, 0.f};
;         acc = __builtin_amdgcn_mfma_f32_16x16x32_bf16(S.bh[nb], uh, acc, 0, 0, 0);
;         *(LAS f32x4*)(tile + fr * TSTR + 16 * nb + 4 * fq) = acc; }
; __device__ __forceinline__ void ssm_pass2(LAS unsigned char* lds, const bf16_t* US, const float* SST, bf16_t* YB, const float* ABAR, const bf16_t* BBH, const bf16_t* BBL, const bf16_t* CMH, const bf16_t* CML, const float* dco, int gw, int NGW, int lane, int wave) {
;     ...
;             ssm_bu_tile(S, uh, tile, lane);
;             if (grp < 15) ssm_u_load(uh, US, tok + 16, g, lane);
;             float ud[4];
; #pragma unroll
;             for (int i = 0; i < 4; ++i) ud[i] = bf_lo((unsigned)US[(size_t)(tok + 4 * fq + i) * SSMW + g * 16 + fr]);
;             float br[16], bi[16];
; #pragma unroll
;             for (int t = 0; t < 16; ++t) { br[t] = tile[t * TSTR + lane]; bi[t] = tile[t * TSTR + 64 + lane]; }
;             asm volatile("s_waitcnt lgkmcnt(0)" ::: "memory");
; #pragma unroll
;             for (int t = 0; t < 16; ++t) { const float nr = S.ar * xr - S.ai * xi + br[t], ni = S.ar * xi + S.ai * xr + bi[t]; xr = nr; xi = ni; br[t] = xr; bi[t] = xi; }
; #pragma unroll
;             for (int t = 0; t < 16; ++t) { tile[t * TSTR + lane] = br[t]; tile[t * TSTR + 64 + lane] = bi[t]; }
	v_and_b32_e32 v101, 0xffff, v230
	v_lshrrev_b32_e32 v102, 16, v230
	v_and_b32_e32 v103, 0xffff, v231
	v_lshrrev_b32_e32 v104, 16, v231
	v_lshl_or_b32 v214, v232, 16, v101
	v_and_or_b32 v215, v232, s99, v102
	v_lshl_or_b32 v216, v233, 16, v103
	v_and_or_b32 v217, v233, s99, v104
	v_and_b32_e32 v101, 0xffff, v234
	v_lshrrev_b32_e32 v102, 16, v234
	v_and_b32_e32 v103, 0xffff, v235
	v_lshrrev_b32_e32 v104, 16, v235
	v_lshl_or_b32 v218, v236, 16, v101
	v_and_or_b32 v219, v236, s99, v102
	v_lshl_or_b32 v220, v237, 16, v103
	v_and_or_b32 v221, v237, s99, v104
	v_and_b32_e32 v101, 0xffff, v238
	v_lshrrev_b32_e32 v102, 16, v238
	v_and_b32_e32 v103, 0xffff, v239
	v_lshrrev_b32_e32 v104, 16, v239
	v_lshl_or_b32 v222, v240, 16, v101
	v_and_or_b32 v223, v240, s99, v102
	v_lshl_or_b32 v224, v241, 16, v103
	v_and_or_b32 v225, v241, s99, v104
	v_and_b32_e32 v101, 0xffff, v242
	v_lshrrev_b32_e32 v102, 16, v242
	v_and_b32_e32 v103, 0xffff, v243
	v_lshrrev_b32_e32 v104, 16, v243
	v_lshl_or_b32 v226, v244, 16, v101
	v_and_or_b32 v227, v244, s99, v102
	v_lshl_or_b32 v228, v245, 16, v103
	v_and_or_b32 v229, v245, s99, v104
	v_cndmask_b32_e64 v55, v51, 0, s[6:7]
	v_cndmask_b32_e64 v54, v50, 0, s[6:7]
	v_cndmask_b32_e64 v53, v49, 0, s[6:7]
	v_cndmask_b32_e64 v52, v48, 0, s[6:7]
	v_mov_b32_e32 v48, v56
	v_mov_b32_e32 v49, v57
	v_mov_b32_e32 v50, v58
	v_mov_b32_e32 v51, v59
	v_mfma_f32_16x16x32_bf16 v[160:163], v[52:55], v[16:19], 0
	v_mfma_f32_16x16x32_bf16 v[164:167], v[52:55], v[20:23], 0
	v_mfma_f32_16x16x32_bf16 v[168:171], v[52:55], v[24:27], 0
	v_mfma_f32_16x16x32_bf16 v[172:175], v[52:55], v[28:31], 0
	v_mfma_f32_16x16x32_bf16 v[176:179], v[52:55], v[32:35], 0
	v_mfma_f32_16x16x32_bf16 v[180:183], v[52:55], v[36:39], 0
	v_mfma_f32_16x16x32_bf16 v[184:187], v[52:55], v[40:43], 0
	v_mfma_f32_16x16x32_bf16 v[188:191], v[52:55], v[44:47], 0
	v_mfma_f32_16x16x32_bf16 v[156:159], v[52:55], v[152:155], 0
	ds_write_b128 v144, v[160:163]
	ds_write_b128 v144, v[164:167] offset:1280
	ds_write_b128 v144, v[168:171] offset:2560
	ds_write_b128 v144, v[172:175] offset:3840
	ds_write_b128 v144, v[176:179] offset:5120
	ds_write_b128 v144, v[180:183] offset:6400
	ds_write_b128 v144, v[184:187] offset:7680
	ds_write_b128 v144, v[188:191] offset:8960
.Lssm2_grp:
	s_waitcnt lgkmcnt(0)
	ds_read_b128 v[0:3], v145
	ds_read_b128 v[60:63], v145 offset:5120
	ds_read_b128 v[4:7], v145 offset:16
	ds_read_b128 v[64:67], v145 offset:5136
	ds_read_b128 v[8:11], v145 offset:32
	ds_read_b128 v[68:71], v145 offset:5152
	ds_read_b128 v[12:15], v145 offset:48
	ds_read_b128 v[72:75], v145 offset:5168
	v_mov_b32_e32 v232, v156
	v_mov_b32_e32 v233, v157
	v_mov_b32_e32 v234, v158
	v_mov_b32_e32 v235, v159
	v_cndmask_b32_e64 v55, v51, 0, s[6:7]
	v_cndmask_b32_e64 v54, v50, 0, s[6:7]
	v_cndmask_b32_e64 v53, v49, 0, s[6:7]
	v_cndmask_b32_e64 v52, v48, 0, s[6:7]
	global_load_dwordx4 v[48:51], v[148:149], off
	v_lshl_add_u64 v[148:149], v[148:149], 0, s[100:101]
	v_mfma_f32_16x16x32_bf16 v[160:163], v[52:55], v[16:19], 0
	v_mfma_f32_16x16x32_bf16 v[164:167], v[52:55], v[20:23], 0
	v_mfma_f32_16x16x32_bf16 v[168:171], v[52:55], v[24:27], 0
	v_mfma_f32_16x16x32_bf16 v[172:175], v[52:55], v[28:31], 0
	v_mfma_f32_16x16x32_bf16 v[176:179], v[52:55], v[32:35], 0
	v_mfma_f32_16x16x32_bf16 v[180:183], v[52:55], v[36:39], 0
	v_mfma_f32_16x16x32_bf16 v[184:187], v[52:55], v[40:43], 0
	v_mfma_f32_16x16x32_bf16 v[188:191], v[52:55], v[44:47], 0
	v_mfma_f32_16x16x32_bf16 v[156:159], v[52:55], v[152:155], 0
	s_waitcnt lgkmcnt(6)
	v_fmac_f32_e32 v0, v90, v100
	v_fmac_f32_e32 v60, v90, v76
	v_fmac_f32_e32 v0, v77, v76
	v_fmac_f32_e32 v60, v91, v100
	v_fmac_f32_e32 v1, v90, v0
	v_fmac_f32_e32 v61, v90, v60
	v_fmac_f32_e32 v1, v77, v60
	v_fmac_f32_e32 v61, v91, v0
	v_cvt_pk_bf16_f32 v128, v0, v60
	ds_write_b32 v146, v128
	v_fmac_f32_e32 v2, v90, v1
	v_fmac_f32_e32 v62, v90, v61
	v_fmac_f32_e32 v2, v77, v61
	v_fmac_f32_e32 v62, v91, v1
	v_cvt_pk_bf16_f32 v129, v1, v61
	ds_write_b32 v146, v129 offset:288
	v_fmac_f32_e32 v3, v90, v2
	v_fmac_f32_e32 v63, v90, v62
	v_fmac_f32_e32 v3, v77, v62
	v_fmac_f32_e32 v63, v91, v2
	v_cvt_pk_bf16_f32 v130, v2, v62
	ds_write_b32 v146, v130 offset:576
	s_waitcnt lgkmcnt(7)
	v_fmac_f32_e32 v4, v90, v3
	v_fmac_f32_e32 v64, v90, v63
	v_fmac_f32_e32 v4, v77, v63
	v_fmac_f32_e32 v64, v91, v3
	v_cvt_pk_bf16_f32 v131, v3, v63
	ds_write_b32 v146, v131 offset:864
	v_fmac_f32_e32 v5, v90, v4
	v_fmac_f32_e32 v65, v90, v64
	v_fmac_f32_e32 v5, v77, v64
	v_fmac_f32_e32 v65, v91, v4
	v_cvt_pk_bf16_f32 v132, v4, v64
	ds_write_b32 v146, v132 offset:1152
	v_fmac_f32_e32 v6, v90, v5
	v_fmac_f32_e32 v66, v90, v65
	v_fmac_f32_e32 v6, v77, v65
	v_fmac_f32_e32 v66, v91, v5
	v_cvt_pk_bf16_f32 v133, v5, v65
	ds_write_b32 v146, v133 offset:1440
	v_fmac_f32_e32 v7, v90, v6
	v_fmac_f32_e32 v67, v90, v66
	v_fmac_f32_e32 v7, v77, v66
	v_fmac_f32_e32 v67, v91, v6
	v_cvt_pk_bf16_f32 v134, v6, v66
	ds_write_b32 v146, v134 offset:1728
	s_waitcnt lgkmcnt(9)
; __device__ __forceinline__ unsigned cvt_pk_bf16(float lo, float hi) { unsigned r; asm volatile("v_cvt_pk_bf16_f32 %0, %1, %2" : "=v"(r) : "v"(lo), "v"(hi)); return r; }
; #define LAS __attribute__((address_space(3)))
; __device__ __forceinline__ void ssm_pass2(LAS unsigned char* lds, const bf16_t* US, const float* SST, bf16_t* YB, const float* ABAR, const bf16_t* BBH, const bf16_t* BBL, const bf16_t* CMH, const bf16_t* CML, const float* dco, int gw, int NGW, int lane, int wave) {
;     ...
;             for (int t = 0; t < 16; ++t) { br[t] = tile[t * TSTR + lane]; bi[t] = tile[t * TSTR + 64 + lane]; }
;             asm volatile("s_waitcnt lgkmcnt(0)" ::: "memory");
; #pragma unroll
;             for (int t = 0; t < 16; ++t) { const float nr = S.ar * xr - S.ai * xi + br[t], ni = S.ar * xi + S.ai * xr + bi[t]; xr = nr; xi = ni; br[t] = xr; bi[t] = xi; }
; #pragma unroll
;             for (int t = 0; t < 16; ++t) { tile[t * TSTR + lane] = br[t]; tile[t * TSTR + 64 + lane] = bi[t]; }
;             asm volatile("s_waitcnt lgkmcnt(0)" ::: "memory");
;             f32x4 acc = {0.f, 0.f, 0.f, 0.f}, acc2 = {0.f, 0.f, 0.f, 0.f};
;             f32x4 xa[4][2];
; #pragma unroll
;             for (int ks = 0; ks < 4; ++ks) { xa[ks][0] = *(const LAS f32x4*)(tile + fr * TSTR + ks * 32 + fq * 8); xa[ks][1] = *(const LAS f32x4*)(tile + fr * TSTR + ks * 32 + fq * 8 + 4); }
; #pragma unroll
;             for (int ks = 0; ks < 4; ++ks) { const f32x4 x0 = xa[ks][0], x1 = xa[ks][1]; u32x4 h;
;                 h.x = cvt_pk_bf16(x0[0], x0[1]); h.y = cvt_pk_bf16(x0[2], x0[3]); h.z = cvt_pk_bf16(x1[0], x1[1]); h.w = cvt_pk_bf16(x1[2], x1[3]);
;                 const bf16x8 xh = __builtin_bit_cast(bf16x8, h);
;                 if (ks & 1) acc2 = __builtin_amdgcn_mfma_f32_16x16x32_bf16(xh, ch[ks], acc2, 0, 0, 0); else acc = __builtin_amdgcn_mfma_f32_16x16x32_bf16(xh, ch[ks], acc, 0, 0, 0); }
;             acc = acc + acc2;
; #pragma unroll
;             for (int i = 0; i < 4; ++i) { const float y = acc[i] + dh * ud[i];
;                 const unsigned w = cvt_pk_bf16(gelu_tanh(y), 0.f); YB[(size_t)(tok + 4 * fq + i) * SSMW + g * 16 + fr] = (bf16_t)(w & 0xffffu); }
	v_fmac_f32_e32 v8, v90, v7
	v_fmac_f32_e32 v68, v90, v67
	v_fmac_f32_e32 v8, v77, v67
	v_fmac_f32_e32 v68, v91, v7
	v_cvt_pk_bf16_f32 v135, v7, v67
	ds_write_b32 v146, v135 offset:2016
	v_fmac_f32_e32 v9, v90, v8
	v_fmac_f32_e32 v69, v90, v68
	v_fmac_f32_e32 v9, v77, v68
	v_fmac_f32_e32 v69, v91, v8
	v_cvt_pk_bf16_f32 v136, v8, v68
	ds_write_b32 v146, v136 offset:2304
	v_fmac_f32_e32 v10, v90, v9
	v_fmac_f32_e32 v70, v90, v69
	v_fmac_f32_e32 v10, v77, v69
	v_fmac_f32_e32 v70, v91, v9
	v_cvt_pk_bf16_f32 v137, v9, v69
	ds_write_b32 v146, v137 offset:2592
	v_fmac_f32_e32 v11, v90, v10
	v_fmac_f32_e32 v71, v90, v70
	v_fmac_f32_e32 v11, v77, v70
	v_fmac_f32_e32 v71, v91, v10
	v_cvt_pk_bf16_f32 v138, v10, v70
	ds_write_b32 v146, v138 offset:2880
	s_waitcnt lgkmcnt(11)
	v_fmac_f32_e32 v12, v90, v11
	v_fmac_f32_e32 v72, v90, v71
	v_fmac_f32_e32 v12, v77, v71
	v_fmac_f32_e32 v72, v91, v11
	v_cvt_pk_bf16_f32 v139, v11, v71
	ds_write_b32 v146, v139 offset:3168
	v_fmac_f32_e32 v13, v90, v12
	v_fmac_f32_e32 v73, v90, v72
	v_fmac_f32_e32 v13, v77, v72
	v_fmac_f32_e32 v73, v91, v12
	v_cvt_pk_bf16_f32 v140, v12, v72
	ds_write_b32 v146, v140 offset:3456
	v_fmac_f32_e32 v14, v90, v13
	v_fmac_f32_e32 v74, v90, v73
	v_fmac_f32_e32 v14, v77, v73
	v_fmac_f32_e32 v74, v91, v13
	v_cvt_pk_bf16_f32 v141, v13, v73
	ds_write_b32 v146, v141 offset:3744
	v_fmac_f32_e32 v15, v90, v14
	v_fmac_f32_e32 v75, v90, v74
	v_fmac_f32_e32 v15, v77, v74
	v_fmac_f32_e32 v75, v91, v14
	v_cvt_pk_bf16_f32 v142, v14, v74
	ds_write_b32 v146, v142 offset:4032
	v_cvt_pk_bf16_f32 v143, v15, v75
	ds_write_b32 v146, v143 offset:4320
	v_mov_b32_e32 v100, v15
	v_mov_b32_e32 v76, v75
	s_waitcnt lgkmcnt(0)
	ds_read_b128 v[198:201], v147
	ds_read_b128 v[202:205], v147 offset:64
	ds_read_b128 v[206:209], v147 offset:128
	ds_read_b128 v[210:213], v147 offset:192
	ds_write_b128 v144, v[160:163]
	ds_write_b128 v144, v[164:167] offset:1280
	ds_write_b128 v144, v[168:171] offset:2560
	ds_write_b128 v144, v[172:175] offset:3840
	ds_write_b128 v144, v[176:179] offset:5120
	ds_write_b128 v144, v[180:183] offset:6400
	ds_write_b128 v144, v[184:187] offset:7680
	ds_write_b128 v144, v[188:191] offset:8960
	s_waitcnt lgkmcnt(11)
	v_mfma_f32_16x16x32_bf16 v[92:95], v[198:201], v[214:217], 0
	s_waitcnt lgkmcnt(10)
	v_mfma_f32_16x16x32_bf16 v[96:99], v[202:205], v[218:221], 0
	s_waitcnt lgkmcnt(9)
	v_mfma_f32_16x16x32_bf16 v[92:95], v[206:209], v[222:225], v[92:95]
	s_waitcnt lgkmcnt(8)
	v_mfma_f32_16x16x32_bf16 v[96:99], v[210:213], v[226:229], v[96:99]
	s_add_i32 s20, s20, 1
	s_nop 7
	v_pk_add_f32 v[92:93], v[92:93], v[96:97]
	v_fma_f32 v92, v124, v232, v92
	v_mul_f32_e32 v101, 0x3d372713, v92
	v_pk_add_f32 v[94:95], v[94:95], v[98:99]
	v_fmac_f32_e32 v93, v124, v233
	v_mul_f32_e32 v101, v92, v101
	v_fma_f32 v94, v124, v234, v94
	v_mul_f32_e32 v102, 0.5, v92
	v_mul_f32_e32 v103, 0x3d372713, v93
	v_fma_f32 v92, v92, v101, v92
	v_fmac_f32_e32 v95, v124, v235
	v_mul_f32_e32 v105, 0x3d372713, v94
	v_mul_f32_e32 v103, v93, v103
	v_mul_f32_e32 v92, 0x3f4c422a, v92
	v_mul_f32_e32 v104, 0.5, v93
	v_mul_f32_e32 v107, 0x3d372713, v95
	v_mul_f32_e32 v105, v94, v105
	v_fma_f32 v93, v93, v103, v93
	v_mul_f32_e32 v92, 0x4038aa3b, v92
	v_mul_f32_e32 v106, 0.5, v94
	v_mul_f32_e32 v107, v95, v107
	v_fma_f32 v94, v94, v105, v94
	v_mul_f32_e32 v93, 0x3f4c422a, v93
	v_exp_f32_e32 v92, v92
	v_mul_f32_e32 v108, 0.5, v95
	v_fma_f32 v95, v95, v107, v95
	v_mul_f32_e32 v94, 0x3f4c422a, v94
	v_mul_f32_e32 v93, 0x4038aa3b, v93
	v_mul_f32_e32 v95, 0x3f4c422a, v95
	v_mul_f32_e32 v94, 0x4038aa3b, v94
	v_exp_f32_e32 v93, v93
	v_mul_f32_e32 v95, 0x4038aa3b, v95
	v_exp_f32_e32 v94, v94
	v_exp_f32_e32 v95, v95
	v_add_f32_e32 v92, 1.0, v92
	v_rcp_f32_e32 v92, v92
	v_add_f32_e32 v93, 1.0, v93
	v_add_f32_e32 v94, 1.0, v94
	v_rcp_f32_e32 v93, v93
	v_add_f32_e32 v95, 1.0, v95
	v_rcp_f32_e32 v94, v94
	v_rcp_f32_e32 v95, v95
	v_fma_f32 v92, v92, -2.0, 2.0
	v_mul_f32_e32 v92, v102, v92
	v_fma_f32 v93, v93, -2.0, 2.0
	v_cvt_pk_bf16_f32 v92, v92, v81
	v_fma_f32 v94, v94, -2.0, 2.0
	v_mul_f32_e32 v93, v104, v93
	global_store_short v[150:151], v92, off
	v_cvt_pk_bf16_f32 v92, v93, v81
	v_fma_f32 v95, v95, -2.0, 2.0
	v_mul_f32_e32 v94, v106, v94
	global_store_short v[150:151], v92, off offset:1024
	v_cvt_pk_bf16_f32 v92, v94, v81
	v_mul_f32_e32 v95, v108, v95
	global_store_short v[150:151], v92, off offset:2048
	v_cvt_pk_bf16_f32 v92, v95, v81
	global_store_short v[150:151], v92, off offset:3072
	v_lshl_add_u64 v[150:151], v[150:151], 0, s[100:101]
	s_cmp_eq_u32 s20, 16
	s_waitcnt vmcnt(4)
	s_cbranch_scc0 .Lssm2_grp
	s_add_i32 s70, s70, s33
	s_add_i32 s68, s68, s69
	s_cmpk_gt_i32 s70, 0xfff
	s_cbranch_scc0 .LBB0_547
